# v30 + LayerNorm+router phase: gamma/beta loads hoisted out of the token loop
# baseline (speedup 1.0000x reference)
.LBB0_1054:
	global_load_dwordx4 v[6:9], v[2:3], off
	v_add_u32_e32 v1, 0x200, v1
	v_cmp_lt_u32_e32 vcc, s3, v1
	v_lshl_add_u64 v[2:3], v[2:3], 0, s[4:5]
	s_or_b64 s[0:1], vcc, s[0:1]
	s_waitcnt vmcnt(0)
	ds_write_b128 v4, v[6:9]
	v_add_u32_e32 v4, 0x2000, v4
	s_andn2_b64 exec, exec, s[0:1]
	s_cbranch_execnz .LBB0_1054
	s_or_b64 exec, exec, s[0:1]
	s_mov_b64 s[0:1], exec
	v_readlane_b32 s4, v234, 3
	v_readlane_b32 s5, v234, 4
	s_and_b64 s[4:5], s[0:1], s[4:5]
	s_mov_b64 exec, s[4:5]
	v_mov_b32_e32 v1, 0
	ds_write_b32 v184, v1 offset:32768
	s_or_b64 exec, exec, s[0:1]
	s_add_u32 s54, s84, 0x980000
	v_cndmask_b32_e64 v1, 0, 1, s[70:71]
	s_addc_u32 s55, s85, 0
	v_cmp_ne_u32_e64 s[0:1], 1, v1
	s_andn2_b64 vcc, exec, s[70:71]
	s_waitcnt lgkmcnt(0)
	s_barrier
	s_cbranch_vccnz .LBB0_1062
	v_mbcnt_hi_u32_b32 v2, -1, v186
	v_and_b32_e32 v3, 64, v2
	v_add_u32_e32 v3, 64, v3
	v_xor_b32_e32 v4, 1, v2
	v_cmp_lt_i32_e32 vcc, v4, v3
	v_readlane_b32 s4, v234, 7
	v_readlane_b32 s6, v234, 9
	v_cndmask_b32_e32 v4, v2, v4, vcc
	v_lshlrev_b32_e32 v40, 2, v4
	v_xor_b32_e32 v4, 2, v2
	v_cmp_lt_i32_e32 vcc, v4, v3
	v_readlane_b32 s7, v234, 10
	v_readlane_b32 s6, v234, 0
	v_cndmask_b32_e32 v4, v2, v4, vcc
	v_lshlrev_b32_e32 v41, 2, v4
	v_xor_b32_e32 v4, 4, v2
	v_cmp_lt_i32_e32 vcc, v4, v3
	v_ashrrev_i32_e32 v1, 31, v0
	v_readlane_b32 s12, v234, 15
	v_cndmask_b32_e32 v4, v2, v4, vcc
	v_lshlrev_b32_e32 v42, 2, v4
	v_xor_b32_e32 v4, 8, v2
	v_cmp_lt_i32_e32 vcc, v4, v3
	v_readlane_b32 s13, v234, 16
	v_readlane_b32 s14, v234, 17
	v_cndmask_b32_e32 v4, v2, v4, vcc
	v_lshlrev_b32_e32 v43, 2, v4
	v_xor_b32_e32 v4, 16, v2
	v_cmp_lt_i32_e32 vcc, v4, v3
	v_readlane_b32 s15, v234, 18
	v_readlane_b32 s16, v234, 19
	v_cndmask_b32_e32 v4, v2, v4, vcc
	v_lshlrev_b32_e32 v44, 2, v4
	v_xor_b32_e32 v4, 32, v2
	v_cmp_lt_i32_e32 vcc, v4, v3
	v_readlane_b32 s17, v234, 20
	v_readlane_b32 s7, v234, 1
	v_cndmask_b32_e32 v2, v2, v4, vcc
	v_lshlrev_b32_e32 v45, 2, v2
	v_lshlrev_b64 v[2:3], 4, v[0:1]
	v_readlane_b32 s5, v234, 8
	v_readlane_b32 s18, v234, 21
	v_readlane_b32 s19, v234, 22
	s_mov_b64 s[12:13], s[16:17]
	s_lshl_b32 s6, s6, 4
	s_lshl_b32 s7, s86, 1
	s_ashr_i32 s47, s46, 31
	s_mov_b64 s[14:15], s[18:19]
	v_lshl_add_u64 v[4:5], s[12:13], 0, v[2:3]
	s_mov_b64 s[4:5], 0x1000
	s_add_i32 s20, s6, s7
	s_lshl_b64 s[6:7], s[46:47], 10
	v_lshl_add_u64 v[16:17], v[4:5], 0, s[4:5]
	v_lshl_add_u64 v[4:5], s[14:15], 0, v[2:3]
	v_lshl_add_u64 v[20:21], v[0:1], 2, s[6:7]
	s_lshl_b64 s[6:7], s[46:47], 12
	v_lshl_add_u64 v[18:19], v[4:5], 0, s[4:5]
	v_lshlrev_b32_e32 v4, 7, v0
	v_and_b32_e32 v5, 0x3c0, v161
	s_ashr_i32 s81, s80, 31
	v_lshl_add_u64 v[22:23], s[6:7], 0, v[2:3]
	s_lshl_b64 s[6:7], s[46:47], 11
	s_mov_b32 s3, 0
	v_cmp_eq_u32_e64 s[4:5], 0, v0
	v_lshl_add_u32 v46, v5, 2, 0
	s_lshl_b32 s22, s82, 4
	s_lshl_b64 s[24:25], s[80:81], 10
	s_lshl_b64 s[26:27], s[80:81], 12
	v_lshl_add_u64 v[24:25], v[0:1], 3, s[6:7]
	s_lshl_b64 s[28:29], s[80:81], 11
	s_mov_b32 s30, 0x3fb504f3
	v_mov_b32_e32 v47, 0
	v_mov_b32_e32 v48, 0x3727c5ac
	s_mov_b32 s23, 0xf800000
	v_mov_b32_e32 v49, 0x260
	s_mov_b32 s31, 0xc3e00000
	v_mov_b32_e32 v50, 0x43e00000
	s_mov_b32 s36, 0xe400000
	v_add_u32_e32 v51, 0, v4
	v_mov_b32_e32 v52, 1
	s_mov_b32 s37, 0xff61b1e6
	s_mov_b32 s38, 0x3fb8aa3b
	s_mov_b32 s39, 0xc2ce8ed0
	s_mov_b32 s40, 0x42b17218
	v_mov_b32_e32 v53, 0xff61b1e6
	v_mov_b32_e32 v54, 0x7f800000
	s_mov_b32 s41, s46
	v_readlane_b32 s8, v234, 11
	v_readlane_b32 s9, v234, 12
	v_readlane_b32 s10, v234, 13
	v_readlane_b32 s11, v234, 14
	global_load_dwordx4 v[200:203], v[16:17], off
	global_load_dwordx4 v[204:207], v[16:17], off offset:1024
	global_load_dwordx4 v[208:211], v[16:17], off offset:2048
	global_load_dwordx4 v[212:215], v[16:17], off offset:3072
	global_load_dwordx4 v[216:219], v[18:19], off
	global_load_dwordx4 v[220:223], v[18:19], off offset:1024
	global_load_dwordx4 v[224:227], v[18:19], off offset:2048
	global_load_dwordx4 v[228:231], v[18:19], off offset:3072
	s_waitcnt vmcnt(0)
	s_branch .LBB0_1060

.LBB0_1060:
	v_lshl_add_u64 v[0:1], s[84:85], 0, v[24:25]
	v_add_co_u32_e32 v0, vcc, 0x14400000, v0
	s_waitcnt lgkmcnt(6)
	v_lshl_add_u64 v[2:3], s[84:85], 0, v[22:23]
	v_addc_co_u32_e32 v1, vcc, 0, v1, vcc
	global_load_dwordx2 v[4:5], v[0:1], off nt
	s_waitcnt lgkmcnt(0)
	global_load_dwordx2 v[14:15], v[0:1], off offset:512 nt
	global_load_dwordx2 v[28:29], v[0:1], off offset:1024 nt
	v_add_co_u32_e32 v26, vcc, 0x10400000, v2
	global_load_dwordx2 v[30:31], v[0:1], off offset:1536 nt
	s_nop 0
	v_addc_co_u32_e32 v27, vcc, 0, v3, vcc
	global_load_dwordx4 v[0:3], v[26:27], off nt
	global_load_dwordx4 v[6:9], v[26:27], off offset:1024 nt
	global_load_dwordx4 v[10:13], v[26:27], off offset:2048 nt
	global_load_dwordx4 v[56:59], v[26:27], off offset:3072 nt
	s_waitcnt vmcnt(7)
	v_lshlrev_b32_e32 v32, 16, v4
	v_and_b32_e32 v33, 0xffff0000, v4
	v_lshlrev_b32_e32 v4, 16, v5
	v_and_b32_e32 v5, 0xffff0000, v5
	s_waitcnt vmcnt(6)
	v_lshlrev_b32_e32 v34, 16, v14
	v_and_b32_e32 v35, 0xffff0000, v14
	v_lshlrev_b32_e32 v14, 16, v15
	v_and_b32_e32 v15, 0xffff0000, v15
	s_waitcnt vmcnt(5)
	v_lshlrev_b32_e32 v38, 16, v28
	v_and_b32_e32 v39, 0xffff0000, v28
	v_lshlrev_b32_e32 v28, 16, v29
	v_and_b32_e32 v29, 0xffff0000, v29
	s_waitcnt vmcnt(3)
	v_pk_fma_f32 v[4:5], v[2:3], s[30:31], v[4:5] op_sel_hi:[1,0,1]
	v_pk_fma_f32 v[64:65], v[0:1], s[30:31], v[32:33] op_sel_hi:[1,0,1]
	s_waitcnt vmcnt(2)
	v_pk_fma_f32 v[0:1], v[8:9], s[30:31], v[14:15] op_sel_hi:[1,0,1]
	v_pk_fma_f32 v[2:3], v[6:7], s[30:31], v[34:35] op_sel_hi:[1,0,1]
	v_lshlrev_b32_e32 v60, 16, v30
	v_and_b32_e32 v61, 0xffff0000, v30
	v_lshlrev_b32_e32 v62, 16, v31
	v_and_b32_e32 v63, 0xffff0000, v31
	s_waitcnt vmcnt(1)
	v_pk_fma_f32 v[28:29], v[12:13], s[30:31], v[28:29] op_sel_hi:[1,0,1]
	v_pk_fma_f32 v[30:31], v[10:11], s[30:31], v[38:39] op_sel_hi:[1,0,1]
	v_pk_mov_b32 v[6:7], v[64:65], v[4:5] op_sel:[1,0]
	v_mov_b32_e32 v8, v64
	v_mov_b32_e32 v9, v5
	v_pk_mov_b32 v[10:11], v[2:3], v[0:1] op_sel:[1,0]
	v_mov_b32_e32 v12, v2
	v_mov_b32_e32 v13, v1
	v_pk_add_f32 v[6:7], v[6:7], v[8:9]
	v_pk_add_f32 v[8:9], v[10:11], v[12:13]
	s_waitcnt vmcnt(0)
	v_pk_fma_f32 v[32:33], v[58:59], s[30:31], v[62:63] op_sel_hi:[1,0,1]
	v_pk_fma_f32 v[34:35], v[56:57], s[30:31], v[60:61] op_sel_hi:[1,0,1]
	v_add_f32_e32 v12, v6, v7
	v_pk_add_f32 v[6:7], v[8:9], v[8:9] op_sel:[0,1] op_sel_hi:[1,0]
	v_add_f32_e32 v14, v30, v31
	v_add_f32_e32 v38, v28, v29
	v_mov_b32_e32 v57, v34
	v_mov_b32_e32 v15, v32
	v_mov_b32_e32 v39, v33
	v_add_f32_e32 v56, 0, v12
	v_mov_b32_e32 v7, v35
	v_pk_add_f32 v[10:11], v[14:15], v[38:39]
	v_pk_add_f32 v[6:7], v[56:57], v[6:7]
	s_nop 0
	v_pk_add_f32 v[6:7], v[6:7], v[10:11]
	v_add_f32_e32 v6, v6, v7
	ds_bpermute_b32 v7, v40, v6
	s_waitcnt lgkmcnt(0)
	v_add_f32_e32 v6, v6, v7
	ds_bpermute_b32 v7, v41, v6
	s_waitcnt lgkmcnt(0)
	v_add_f32_e32 v6, v6, v7
	ds_bpermute_b32 v7, v42, v6
	s_waitcnt lgkmcnt(0)
	v_add_f32_e32 v6, v6, v7
	ds_bpermute_b32 v7, v43, v6
	s_waitcnt lgkmcnt(0)
	v_add_f32_e32 v6, v6, v7
	ds_bpermute_b32 v7, v44, v6
	s_waitcnt lgkmcnt(0)
	v_add_f32_e32 v6, v6, v7
	ds_bpermute_b32 v7, v45, v6
	s_waitcnt lgkmcnt(0)
	v_add_f32_e32 v6, v6, v7
	v_fmamk_f32 v65, v6, 0xba800000, v65
	v_fmac_f32_e32 v64, 0xba800000, v6
	v_fmamk_f32 v5, v6, 0xba800000, v5
	v_fmac_f32_e32 v4, 0xba800000, v6
	v_fmamk_f32 v3, v6, 0xba800000, v3
	v_fmac_f32_e32 v2, 0xba800000, v6
	v_fmamk_f32 v1, v6, 0xba800000, v1
	v_fmac_f32_e32 v0, 0xba800000, v6
	v_fmamk_f32 v31, v6, 0xba800000, v31
	v_fmac_f32_e32 v30, 0xba800000, v6
	v_fmamk_f32 v29, v6, 0xba800000, v29
	v_fmac_f32_e32 v28, 0xba800000, v6
	v_fmamk_f32 v33, v6, 0xba800000, v33
	v_fmac_f32_e32 v32, 0xba800000, v6
	v_fmamk_f32 v35, v6, 0xba800000, v35
	v_fmac_f32_e32 v34, 0xba800000, v6
	v_pk_mul_f32 v[6:7], v[4:5], v[4:5]
	v_pk_mul_f32 v[38:39], v[64:65], v[64:65]
	v_pk_mul_f32 v[56:57], v[0:1], v[0:1]
	v_pk_mul_f32 v[58:59], v[2:3], v[2:3]
	v_pk_mov_b32 v[62:63], v[38:39], v[6:7] op_sel:[1,0]
	v_mov_b32_e32 v39, v7
	v_pk_mov_b32 v[6:7], v[58:59], v[56:57] op_sel:[1,0]
	v_mov_b32_e32 v59, v57
	v_mul_f32_e32 v36, v30, v30
	v_mul_f32_e32 v60, v28, v28
	v_pk_add_f32 v[38:39], v[62:63], v[38:39]
	v_pk_add_f32 v[6:7], v[6:7], v[58:59]
	v_pk_fma_f32 v[56:57], v[30:31], v[30:31], v[36:37] op_sel_hi:[1,1,0]
	v_pk_fma_f32 v[60:61], v[28:29], v[28:29], v[60:61] op_sel_hi:[1,1,0]
	v_pk_add_f32 v[38:39], v[38:39], v[38:39] op_sel_hi:[0,1]
	v_pk_add_f32 v[6:7], v[6:7], v[6:7] op_sel_hi:[0,1]
	v_mul_f32_e32 v56, v34, v34
	v_mul_f32_e32 v60, v35, v35
	v_mul_f32_e32 v38, v32, v32
	v_mul_f32_e32 v6, v33, v33
	v_pk_add_f32 v[56:57], v[56:57], v[60:61]
	v_pk_add_f32 v[6:7], v[38:39], v[6:7]
	v_mov_b32_e32 v58, 0
	v_pk_add_f32 v[6:7], v[56:57], v[6:7]
	v_mov_b32_e32 v57, 0
	v_add_f32_e32 v6, v6, v7
	ds_bpermute_b32 v7, v40, v6
	v_mov_b32_e32 v56, 0
	s_waitcnt lgkmcnt(0)
	v_add_f32_e32 v6, v6, v7
	ds_bpermute_b32 v7, v41, v6
	s_waitcnt lgkmcnt(0)
	v_add_f32_e32 v6, v6, v7
	ds_bpermute_b32 v7, v42, v6
	s_waitcnt lgkmcnt(0)
	v_add_f32_e32 v6, v6, v7
	ds_bpermute_b32 v7, v43, v6
	s_waitcnt lgkmcnt(0)
	v_add_f32_e32 v6, v6, v7
	ds_bpermute_b32 v7, v44, v6
	s_waitcnt lgkmcnt(0)
	v_add_f32_e32 v6, v6, v7
	ds_bpermute_b32 v7, v45, v6
	s_waitcnt lgkmcnt(0)
	v_add_f32_e32 v6, v6, v7
	v_fmamk_f32 v6, v6, 0x3a800000, v48
	v_mul_f32_e32 v7, 0x4f800000, v6
	v_cmp_gt_f32_e32 vcc, s23, v6
	s_nop 1
	v_cndmask_b32_e32 v6, v6, v7, vcc
	v_sqrt_f32_e32 v7, v6
	s_nop 0
	v_add_u32_e32 v36, -1, v7
	v_add_u32_e32 v38, 1, v7
	v_fma_f32 v39, -v36, v7, v6
	v_fma_f32 v55, -v38, v7, v6
	v_cmp_ge_f32_e64 s[6:7], 0, v39
	s_nop 1
	v_cndmask_b32_e64 v7, v7, v36, s[6:7]
	v_cmp_lt_f32_e64 s[6:7], 0, v55
	s_nop 1
	v_cndmask_b32_e64 v7, v7, v38, s[6:7]
	v_mul_f32_e32 v36, 0x37800000, v7
	v_cndmask_b32_e32 v7, v7, v36, vcc
	v_cmp_class_f32_e32 vcc, v6, v49
	s_nop 1
	v_cndmask_b32_e32 v6, v7, v6, vcc
	v_div_scale_f32 v7, s[6:7], v6, v6, 1.0
	v_rcp_f32_e32 v36, v7
	v_div_scale_f32 v38, vcc, 1.0, v6, 1.0
	v_fma_f32 v39, -v7, v36, 1.0
	v_fmac_f32_e32 v36, v39, v36
	v_mul_f32_e32 v39, v38, v36
	v_fma_f32 v55, -v7, v39, v38
	v_fmac_f32_e32 v39, v55, v36
	v_fma_f32 v7, -v7, v39, v38
	v_div_fmas_f32 v7, v7, v36, v39
	v_div_fixup_f32 v36, v7, v6, 1.0
	v_pk_mul_f32 v[38:39], v[64:65], v[36:37] op_sel_hi:[1,0]
	v_pk_mul_f32 v[4:5], v[4:5], v[36:37] op_sel_hi:[1,0]
	v_pk_mul_f32 v[0:1], v[0:1], v[36:37] op_sel_hi:[1,0]
	v_pk_fma_f32 v[6:7], v[202:203], v[4:5], v[218:219]
	v_pk_fma_f32 v[4:5], v[200:201], v[38:39], v[216:217]
	global_store_dwordx4 v[26:27], v[4:7], off nt
	v_pk_mul_f32 v[38:39], v[2:3], v[36:37] op_sel_hi:[1,0]
	v_pk_mul_f32 v[30:31], v[30:31], v[36:37] op_sel_hi:[1,0]
	v_pk_mul_f32 v[28:29], v[28:29], v[36:37] op_sel_hi:[1,0]
	v_pk_mul_f32 v[34:35], v[34:35], v[36:37] op_sel_hi:[1,0]
	v_pk_mul_f32 v[32:33], v[32:33], v[36:37] op_sel_hi:[1,0]
	v_med3_f32 v36, v4, s31, v50
	v_med3_f32 v59, v5, s31, v50
	v_med3_f32 v187, v6, s31, v50
	v_med3_f32 v196, v7, s31, v50
	v_mov_b32_e32 v55, 0
	v_cvt_pk_fp8_f32 v55, v36, v59
	v_cvt_pk_fp8_f32 v55, v187, v196 op_sel:[0,0,1]
	v_pk_fma_f32 v[2:3], v[206:207], v[0:1], v[222:223]
	v_pk_fma_f32 v[0:1], v[204:205], v[38:39], v[220:221]
	global_store_dwordx4 v[26:27], v[0:3], off offset:1024 nt
	ds_read_b128 v[60:63], v51
	ds_read_b128 v[64:67], v51 offset:16
	ds_read_b128 v[68:71], v51 offset:32
	ds_read_b128 v[72:75], v51 offset:48
	ds_read_b128 v[76:79], v51 offset:64
	ds_read_b128 v[80:83], v51 offset:80
	ds_read_b128 v[84:87], v51 offset:96
	ds_read_b128 v[88:91], v51 offset:112
	ds_read_b128 v[92:95], v51 offset:8192
	ds_read_b128 v[96:99], v51 offset:8208
	ds_read_b128 v[100:103], v51 offset:8224
	ds_read_b128 v[104:107], v51 offset:8240
	ds_read_b128 v[108:111], v51 offset:8256
	ds_read_b128 v[112:115], v51 offset:8272
	ds_read_b128 v[116:119], v51 offset:8288
	ds_read_b128 v[120:123], v51 offset:8304
	ds_read_b128 v[124:127], v51 offset:16384
	ds_read_b128 v[128:131], v51 offset:16400
	ds_read_b128 v[132:135], v51 offset:16416
	ds_read_b128 v[136:139], v51 offset:16432
	ds_read_b128 v[140:143], v51 offset:16448
	ds_read_b128 v[144:147], v51 offset:16464
	ds_read_b128 v[148:151], v51 offset:16480
	ds_read_b128 v[152:155], v51 offset:16496
	ds_read_b128 v[156:159], v51 offset:24576
	ds_read_b128 v[164:167], v51 offset:24592
	ds_read_b128 v[168:171], v51 offset:24608
	ds_read_b128 v[172:175], v51 offset:24624
	ds_read_b128 v[176:179], v51 offset:24640
	ds_read_b128 v[180:183], v51 offset:24656
	ds_read_b128 v[188:191], v51 offset:24672
	ds_read_b128 v[192:195], v51 offset:24688
	s_waitcnt lgkmcnt(14)
	v_fma_f32 v62, v62, v4, 0
	v_fma_f32 v63, v63, v4, 0
	v_fma_f32 v64, v64, v4, 0
	v_fma_f32 v65, v65, v4, 0
	v_fma_f32 v66, v66, v4, 0
	v_fma_f32 v67, v67, v4, 0
	v_pk_fma_f32 v[60:61], v[60:61], v[4:5], 0 op_sel_hi:[1,0,0]
	v_fmac_f32_e32 v62, v70, v5
	v_fmac_f32_e32 v63, v71, v5
	v_fmac_f32_e32 v64, v72, v5
	v_fmac_f32_e32 v65, v73, v5
	v_fmac_f32_e32 v66, v74, v5
	v_fmac_f32_e32 v67, v75, v5
	v_pk_fma_f32 v[4:5], v[68:69], v[4:5], v[60:61] op_sel:[0,1,0]
	v_fmac_f32_e32 v62, v78, v6
	v_fmac_f32_e32 v63, v79, v6
	v_fmac_f32_e32 v64, v80, v6
	v_fmac_f32_e32 v65, v81, v6
	v_fmac_f32_e32 v66, v82, v6
	v_fmac_f32_e32 v67, v83, v6
	v_pk_fma_f32 v[4:5], v[76:77], v[6:7], v[4:5] op_sel_hi:[1,0,1]
	v_fmac_f32_e32 v62, v7, v86
	v_fmac_f32_e32 v63, v7, v87
	v_fmac_f32_e32 v64, v7, v88
	v_fmac_f32_e32 v65, v7, v89
	v_fmac_f32_e32 v66, v7, v90
	v_fmac_f32_e32 v67, v7, v91
	v_pk_fma_f32 v[4:5], v[6:7], v[84:85], v[4:5] op_sel:[1,0,0]
	v_fmac_f32_e32 v62, v0, v94
	v_fmac_f32_e32 v63, v0, v95
	v_fmac_f32_e32 v64, v0, v96
	v_fmac_f32_e32 v65, v0, v97
	v_fmac_f32_e32 v66, v0, v98
	v_fmac_f32_e32 v67, v0, v99
	v_pk_fma_f32 v[4:5], v[0:1], v[92:93], v[4:5] op_sel_hi:[0,1,1]
	v_med3_f32 v6, v0, s31, v50
	v_med3_f32 v7, v1, s31, v50
	v_fmac_f32_e32 v62, v1, v102
	v_fmac_f32_e32 v63, v1, v103
	v_fmac_f32_e32 v64, v1, v104
	v_fmac_f32_e32 v65, v1, v105
	v_fmac_f32_e32 v66, v1, v106
	v_fmac_f32_e32 v67, v1, v107
	v_pk_fma_f32 v[0:1], v[0:1], v[100:101], v[4:5] op_sel:[1,0,0]
	v_fmac_f32_e32 v62, v2, v110
	v_fmac_f32_e32 v63, v2, v111
	v_fmac_f32_e32 v64, v2, v112
	v_fmac_f32_e32 v65, v2, v113
	v_fmac_f32_e32 v66, v2, v114
	v_fmac_f32_e32 v67, v2, v115
	v_pk_fma_f32 v[0:1], v[2:3], v[108:109], v[0:1] op_sel_hi:[0,1,1]
	v_fmac_f32_e32 v62, v3, v118
	v_fmac_f32_e32 v63, v3, v119
	v_fmac_f32_e32 v64, v3, v120
	v_fmac_f32_e32 v65, v3, v121
	v_fmac_f32_e32 v66, v3, v122
	v_fmac_f32_e32 v67, v3, v123
	v_pk_fma_f32 v[0:1], v[2:3], v[116:117], v[0:1] op_sel:[1,0,0]
	v_med3_f32 v36, v2, s31, v50
	v_med3_f32 v59, v3, s31, v50
	v_cvt_pk_fp8_f32 v56, v6, v7
	v_lshl_add_u64 v[38:39], s[84:85], 0, v[20:21]
	v_add_co_u32_e32 v38, vcc, s36, v38
	v_cvt_pk_fp8_f32 v56, v36, v59 op_sel:[0,0,1]
	s_nop 0
	v_addc_co_u32_e32 v39, vcc, 0, v39, vcc
	v_pk_fma_f32 v[10:11], v[210:211], v[28:29], v[226:227]
	v_pk_fma_f32 v[8:9], v[208:209], v[30:31], v[224:225]
	global_store_dwordx4 v[26:27], v[8:11], off offset:2048 nt
	v_med3_f32 v2, v8, s31, v50
	v_med3_f32 v3, v9, s31, v50
	v_fmac_f32_e32 v62, v8, v126
	v_fmac_f32_e32 v63, v8, v127
	v_fmac_f32_e32 v64, v8, v128
	v_fmac_f32_e32 v65, v8, v129
	v_fmac_f32_e32 v66, v8, v130
	v_fmac_f32_e32 v67, v8, v131
	v_pk_fma_f32 v[0:1], v[8:9], v[124:125], v[0:1] op_sel_hi:[0,1,1]
	v_cvt_pk_fp8_f32 v57, v2, v3
	s_waitcnt lgkmcnt(13)
	v_pk_fma_f32 v[0:1], v[8:9], v[132:133], v[0:1] op_sel:[1,0,0]
	v_fmac_f32_e32 v62, v9, v134
	v_fmac_f32_e32 v63, v9, v135
	s_waitcnt lgkmcnt(12)
	v_fmac_f32_e32 v64, v9, v136
	v_fmac_f32_e32 v65, v9, v137
	v_fmac_f32_e32 v66, v9, v138
	v_fmac_f32_e32 v67, v9, v139
	s_waitcnt lgkmcnt(11)
	v_fmac_f32_e32 v62, v10, v142
	v_fmac_f32_e32 v63, v10, v143
	s_waitcnt lgkmcnt(10)
	v_fmac_f32_e32 v64, v10, v144
	v_fmac_f32_e32 v65, v10, v145
	v_fmac_f32_e32 v66, v10, v146
	v_fmac_f32_e32 v67, v10, v147
	v_pk_fma_f32 v[0:1], v[10:11], v[140:141], v[0:1] op_sel_hi:[0,1,1]
	s_waitcnt lgkmcnt(9)
	v_fmac_f32_e32 v62, v11, v150
	v_fmac_f32_e32 v63, v11, v151
	s_waitcnt lgkmcnt(8)
	v_fmac_f32_e32 v64, v11, v152
	v_fmac_f32_e32 v65, v11, v153
	v_fmac_f32_e32 v66, v11, v154
	v_fmac_f32_e32 v67, v11, v155
	v_pk_fma_f32 v[4:5], v[10:11], v[148:149], v[0:1] op_sel:[1,0,0]
	v_med3_f32 v6, v10, s31, v50
	v_med3_f32 v7, v11, s31, v50
	v_cvt_pk_fp8_f32 v57, v6, v7 op_sel:[0,0,1]
	v_pk_fma_f32 v[0:1], v[212:213], v[34:35], v[228:229]
	v_pk_fma_f32 v[2:3], v[214:215], v[32:33], v[230:231]
	s_waitcnt lgkmcnt(7)
	v_fmac_f32_e32 v62, v0, v158
	v_fmac_f32_e32 v63, v0, v159
	s_waitcnt lgkmcnt(6)
	v_fmac_f32_e32 v64, v0, v164
	v_fmac_f32_e32 v65, v0, v165
	v_fmac_f32_e32 v66, v0, v166
	v_fmac_f32_e32 v67, v0, v167
	v_pk_fma_f32 v[4:5], v[0:1], v[156:157], v[4:5] op_sel_hi:[0,1,1]
	global_store_dwordx4 v[26:27], v[0:3], off offset:3072 nt
	v_med3_f32 v6, v0, s31, v50
	v_med3_f32 v7, v1, s31, v50
	s_waitcnt lgkmcnt(5)
	v_fmac_f32_e32 v62, v1, v170
	v_fmac_f32_e32 v63, v1, v171
	s_waitcnt lgkmcnt(4)
	v_fmac_f32_e32 v64, v1, v172
	v_fmac_f32_e32 v65, v1, v173
	v_fmac_f32_e32 v66, v1, v174
	v_fmac_f32_e32 v67, v1, v175
	v_pk_fma_f32 v[0:1], v[0:1], v[168:169], v[4:5] op_sel:[1,0,0]
	s_waitcnt lgkmcnt(3)
	v_fmac_f32_e32 v62, v2, v178
	v_fmac_f32_e32 v63, v2, v179
	s_waitcnt lgkmcnt(2)
	v_fmac_f32_e32 v64, v2, v180
	v_fmac_f32_e32 v65, v2, v181
	v_fmac_f32_e32 v66, v2, v182
	v_fmac_f32_e32 v67, v2, v183
	v_pk_fma_f32 v[0:1], v[2:3], v[176:177], v[0:1] op_sel_hi:[0,1,1]
	s_waitcnt lgkmcnt(1)
	v_fmac_f32_e32 v62, v3, v190
	v_fmac_f32_e32 v63, v3, v191
	s_waitcnt lgkmcnt(0)
	v_fmac_f32_e32 v64, v3, v192
	v_fmac_f32_e32 v65, v3, v193
	v_fmac_f32_e32 v66, v3, v194
	v_fmac_f32_e32 v67, v3, v195
	v_pk_fma_f32 v[0:1], v[2:3], v[188:189], v[0:1] op_sel:[1,0,0]
	v_med3_f32 v8, v2, s31, v50
	v_med3_f32 v9, v3, s31, v50
	v_cvt_pk_fp8_f32 v58, v6, v7
	ds_bpermute_b32 v2, v40, v0
	ds_bpermute_b32 v3, v40, v1
	ds_bpermute_b32 v4, v40, v62
	ds_bpermute_b32 v5, v40, v63
	ds_bpermute_b32 v6, v40, v64
	ds_bpermute_b32 v7, v40, v65
	ds_bpermute_b32 v10, v40, v66
	ds_bpermute_b32 v11, v40, v67
	v_cvt_pk_fp8_f32 v58, v8, v9 op_sel:[0,0,1]
	s_waitcnt lgkmcnt(6)
	v_pk_add_f32 v[0:1], v[0:1], v[2:3]
	s_waitcnt lgkmcnt(5)
	v_add_f32_e32 v4, v62, v4
	s_waitcnt lgkmcnt(4)
	v_add_f32_e32 v5, v63, v5
	s_waitcnt lgkmcnt(3)
	v_add_f32_e32 v6, v64, v6
	s_waitcnt lgkmcnt(2)
	v_add_f32_e32 v7, v65, v7
	s_waitcnt lgkmcnt(1)
	v_add_f32_e32 v8, v66, v10
	s_waitcnt lgkmcnt(0)
	v_add_f32_e32 v9, v67, v11
	ds_bpermute_b32 v2, v41, v0
	ds_bpermute_b32 v3, v41, v1
	ds_bpermute_b32 v10, v41, v4
	ds_bpermute_b32 v11, v41, v5
	ds_bpermute_b32 v12, v41, v6
	ds_bpermute_b32 v13, v41, v7
	ds_bpermute_b32 v14, v41, v8
	ds_bpermute_b32 v15, v41, v9
	s_waitcnt lgkmcnt(6)
	v_pk_add_f32 v[0:1], v[0:1], v[2:3]
	s_waitcnt lgkmcnt(5)
	v_add_f32_e32 v4, v4, v10
	s_waitcnt lgkmcnt(4)
	v_add_f32_e32 v5, v5, v11
	s_waitcnt lgkmcnt(3)
	v_add_f32_e32 v6, v6, v12
	s_waitcnt lgkmcnt(2)
	v_add_f32_e32 v7, v7, v13
	s_waitcnt lgkmcnt(1)
	v_add_f32_e32 v8, v8, v14
	s_waitcnt lgkmcnt(0)
	v_add_f32_e32 v9, v9, v15
	ds_bpermute_b32 v2, v42, v0
	ds_bpermute_b32 v3, v42, v1
	ds_bpermute_b32 v10, v42, v4
	ds_bpermute_b32 v11, v42, v5
	ds_bpermute_b32 v12, v42, v6
	ds_bpermute_b32 v13, v42, v7
	ds_bpermute_b32 v14, v42, v8
	ds_bpermute_b32 v15, v42, v9
	s_waitcnt lgkmcnt(6)
	v_pk_add_f32 v[0:1], v[0:1], v[2:3]
	s_waitcnt lgkmcnt(5)
	v_add_f32_e32 v4, v4, v10
	s_waitcnt lgkmcnt(4)
	v_add_f32_e32 v5, v5, v11
	s_waitcnt lgkmcnt(3)
	v_add_f32_e32 v6, v6, v12
	s_waitcnt lgkmcnt(2)
	v_add_f32_e32 v7, v7, v13
	s_waitcnt lgkmcnt(1)
	v_add_f32_e32 v8, v8, v14
	s_waitcnt lgkmcnt(0)
	v_add_f32_e32 v9, v9, v15
	ds_bpermute_b32 v2, v43, v0
	ds_bpermute_b32 v3, v43, v1
	ds_bpermute_b32 v10, v43, v4
	ds_bpermute_b32 v11, v43, v5
	ds_bpermute_b32 v12, v43, v6
	ds_bpermute_b32 v13, v43, v7
	ds_bpermute_b32 v14, v43, v8
	ds_bpermute_b32 v15, v43, v9
	s_waitcnt lgkmcnt(6)
	v_pk_add_f32 v[0:1], v[0:1], v[2:3]
	s_waitcnt lgkmcnt(5)
	v_add_f32_e32 v4, v4, v10
	s_waitcnt lgkmcnt(4)
	v_add_f32_e32 v5, v5, v11
	s_waitcnt lgkmcnt(3)
	v_add_f32_e32 v6, v6, v12
	s_waitcnt lgkmcnt(2)
	v_add_f32_e32 v7, v7, v13
	s_waitcnt lgkmcnt(1)
	v_add_f32_e32 v8, v8, v14
	s_waitcnt lgkmcnt(0)
	v_add_f32_e32 v10, v9, v15
	ds_bpermute_b32 v2, v44, v0
	ds_bpermute_b32 v3, v44, v1
	ds_bpermute_b32 v9, v44, v4
	ds_bpermute_b32 v11, v44, v5
	ds_bpermute_b32 v12, v44, v6
	ds_bpermute_b32 v13, v44, v7
	ds_bpermute_b32 v14, v44, v8
	ds_bpermute_b32 v15, v44, v10
	s_waitcnt lgkmcnt(6)
	v_pk_add_f32 v[0:1], v[0:1], v[2:3]
	s_waitcnt lgkmcnt(5)
	v_add_f32_e32 v4, v4, v9
	s_waitcnt lgkmcnt(4)
	v_add_f32_e32 v5, v5, v11
	s_waitcnt lgkmcnt(3)
	v_add_f32_e32 v6, v6, v12
	s_waitcnt lgkmcnt(2)
	v_add_f32_e32 v7, v7, v13
	s_waitcnt lgkmcnt(1)
	v_add_f32_e32 v9, v8, v14
	s_waitcnt lgkmcnt(0)
	v_add_f32_e32 v11, v10, v15
	ds_bpermute_b32 v2, v45, v0
	ds_bpermute_b32 v3, v45, v1
	ds_bpermute_b32 v8, v45, v4
	ds_bpermute_b32 v10, v45, v5
	ds_bpermute_b32 v12, v45, v6
	ds_bpermute_b32 v13, v45, v7
	ds_bpermute_b32 v14, v45, v9
	ds_bpermute_b32 v15, v45, v11
	global_store_dword v[38:39], v55, off
	global_store_dword v[38:39], v56, off offset:256
	global_store_dword v[38:39], v57, off offset:512
	global_store_dword v[38:39], v58, off offset:768
	s_and_saveexec_b64 s[34:35], s[4:5]
	s_cbranch_execz .LBB0_1059
	s_waitcnt lgkmcnt(6)
	v_pk_add_f32 v[2:3], v[0:1], v[2:3]
	s_waitcnt lgkmcnt(5)
	v_add_f32_e32 v4, v4, v8
	v_cmp_gt_f32_e32 vcc, v3, v2
	s_waitcnt lgkmcnt(4)
	v_add_f32_e32 v5, v5, v10
	s_waitcnt lgkmcnt(3)
	v_add_f32_e32 v6, v6, v12
	v_cndmask_b32_e32 v0, v2, v3, vcc
	v_cmp_gt_f32_e64 s[6:7], v4, v0
	s_waitcnt lgkmcnt(2)
	v_add_f32_e32 v7, v7, v13
	s_waitcnt lgkmcnt(1)
	v_add_f32_e32 v9, v9, v14
	v_cndmask_b32_e64 v0, v0, v4, s[6:7]
	v_cmp_gt_f32_e64 s[8:9], v5, v0
	s_waitcnt lgkmcnt(0)
	v_add_f32_e32 v11, v11, v15
	v_cmp_lt_f32_e64 s[18:19], s37, v2
	v_cndmask_b32_e64 v0, v0, v5, s[8:9]
	v_cmp_gt_f32_e64 s[10:11], v6, v0
	s_ashr_i32 s21, s20, 31
	s_nop 0
	v_cndmask_b32_e64 v0, v0, v6, s[10:11]
	v_cmp_gt_f32_e64 s[12:13], v7, v0
	s_nop 1
	v_cndmask_b32_e64 v0, v0, v7, s[12:13]
	v_cmp_gt_f32_e64 s[14:15], v9, v0
	s_nop 1
	v_cndmask_b32_e64 v1, v0, v9, s[14:15]
	v_cndmask_b32_e64 v0, 0, 1, vcc
	v_cndmask_b32_e64 v0, v0, 2, s[6:7]
	v_cndmask_b32_e64 v0, v0, 3, s[8:9]
	v_cndmask_b32_e64 v0, v0, 4, s[10:11]
	v_cndmask_b32_e64 v0, v0, 5, s[12:13]
	v_cndmask_b32_e64 v0, v0, 6, s[14:15]
	v_cmp_ngt_f32_e32 vcc, v11, v1
	s_and_b64 s[42:43], s[14:15], vcc
	s_nop 0
	v_cndmask_b32_e32 v0, 7, v0, vcc
	v_cmp_ne_u32_e64 s[16:17], 0, v0
	s_and_b64 s[16:17], s[16:17], s[18:19]
	v_cmp_ne_u32_e64 s[14:15], 1, v0
	v_cndmask_b32_e64 v2, v53, v2, s[16:17]
	v_cmp_gt_f32_e64 s[16:17], v3, v2
	s_and_b64 s[14:15], s[14:15], s[16:17]
	v_cndmask_b32_e64 v2, v2, v3, s[14:15]
	v_cmp_ne_u32_e64 s[12:13], 2, v0
	v_cmp_gt_f32_e64 s[16:17], v4, v2
	s_and_b64 s[12:13], s[12:13], s[16:17]
	v_cndmask_b32_e64 v2, v2, v4, s[12:13]
	v_cmp_ne_u32_e64 s[10:11], 3, v0
	v_cmp_gt_f32_e64 s[16:17], v5, v2
	s_and_b64 s[10:11], s[10:11], s[16:17]
	v_cndmask_b32_e64 v2, v2, v5, s[10:11]
	v_cmp_ne_u32_e64 s[8:9], 4, v0
	v_cmp_gt_f32_e64 s[16:17], v6, v2
	s_and_b64 s[8:9], s[8:9], s[16:17]
	v_cndmask_b32_e64 v2, v2, v6, s[8:9]
	v_cmp_ne_u32_e64 s[6:7], 5, v0
	v_cmp_gt_f32_e64 s[16:17], v7, v2
	s_and_b64 s[6:7], s[6:7], s[16:17]
	v_cndmask_b32_e64 v2, v2, v7, s[6:7]
	v_cmp_ngt_f32_e64 s[16:17], v9, v2
	s_or_b64 s[16:17], s[42:43], s[16:17]
	v_cndmask_b32_e32 v1, v11, v1, vcc
	v_cndmask_b32_e64 v2, v9, v2, s[16:17]
	v_cmp_gt_f32_e64 s[18:19], v11, v2
	s_and_b64 s[18:19], vcc, s[18:19]
	v_cndmask_b32_e64 v3, 0, 1, s[14:15]
	v_cndmask_b32_e64 v2, v2, v11, s[18:19]
	v_sub_f32_e32 v4, v2, v1
	v_mul_f32_e32 v1, 0x3fb8aa3b, v4
	v_fma_f32 v2, v4, s38, -v1
	v_rndne_f32_e32 v5, v1
	v_fmac_f32_e32 v2, 0x32a5705f, v4
	v_sub_f32_e32 v1, v1, v5
	v_add_f32_e32 v1, v1, v2
	v_cndmask_b32_e64 v3, v3, 2, s[12:13]
	v_exp_f32_e32 v1, v1
	v_cvt_i32_f32_e32 v5, v5
	v_cndmask_b32_e64 v3, v3, 3, s[10:11]
	v_cndmask_b32_e64 v3, v3, 4, s[8:9]
	v_cndmask_b32_e64 v2, v3, 5, s[6:7]
	v_cndmask_b32_e64 v2, 6, v2, s[16:17]
	v_ldexp_f32 v1, v1, v5
	v_cmp_ngt_f32_e32 vcc, s39, v4
	v_cndmask_b32_e64 v2, v2, 7, s[18:19]
	v_lshl_add_u32 v3, v2, 2, 0
	v_cndmask_b32_e32 v5, 0, v1, vcc
	v_lshl_add_u32 v1, v0, 2, 0
	ds_add_rtn_u32 v1, v1, v52 offset:32768
	ds_add_rtn_u32 v3, v3, v52 offset:32768
	v_cmp_nlt_f32_e32 vcc, s40, v4
	s_and_b32 s6, s3, 60
	v_lshl_add_u32 v6, s6, 2, v46
	v_cndmask_b32_e32 v4, v54, v5, vcc
	v_add_f32_e32 v5, 1.0, v4
	s_waitcnt lgkmcnt(0)
	ds_write_b128 v6, v[0:3] offset:32832
	v_div_scale_f32 v0, s[6:7], v5, v5, v4
	v_rcp_f32_e32 v1, v0
	s_lshl_b64 s[6:7], s[20:21], 2
	s_add_u32 s6, s54, s6
	s_addc_u32 s7, s55, s7
	v_fma_f32 v2, -v0, v1, 1.0
	v_fmac_f32_e32 v1, v2, v1
	v_div_scale_f32 v2, vcc, v4, v5, v4
	v_mul_f32_e32 v3, v2, v1
	v_fma_f32 v6, -v0, v3, v2
	v_fmac_f32_e32 v3, v6, v1
	v_fma_f32 v0, -v0, v3, v2
	v_div_scale_f32 v2, s[8:9], v5, v5, 1.0
	v_rcp_f32_e32 v6, v2
	v_div_fmas_f32 v0, v0, v1, v3
	v_div_fixup_f32 v1, v0, v5, v4
	v_fma_f32 v0, -v2, v6, 1.0
	v_fmac_f32_e32 v6, v0, v6
	v_div_scale_f32 v0, vcc, 1.0, v5, 1.0
	v_mul_f32_e32 v3, v0, v6
	v_fma_f32 v4, -v2, v3, v0
	v_fmac_f32_e32 v3, v4, v6
	v_fma_f32 v0, -v2, v3, v0
	v_div_fmas_f32 v0, v0, v6, v3
	v_div_fixup_f32 v0, v0, v5, 1.0
	global_store_dwordx2 v47, v[0:1], s[6:7]
	s_branch .LBB0_1059
